# v12 + ssd full-loop rewrite with duplicated xdt/a LDS layout (one b128 read per 2 steps, no op_sel), lean barrier, mid-loop staging
# speedup vs baseline: 1.0233x; 1.0012x over previous
; __device__ __forceinline__ float bf2f(bf16_t v) { return __uint_as_float(((unsigned)v) << 16); }
; __device__ __forceinline__ float lo2f(unsigned w) { return __uint_as_float(w << 16); }
; __device__ __forceinline__ float hi2f(unsigned w) { return __uint_as_float(w & 0xffff0000u); }
; __device__ __forceinline__ void ssd_scan_unit(CP p, int l, int u, char* smem) {
;     ...
;   auto lwrite = [&](int bi) {
; #pragma unroll
;     for (int x = 0; x < 2; ++x) {
;       const int e = tid + x * 256, tok = e >> 5, rem = e & 31, which = rem >> 4, part = rem & 15;
;       float* d = buf + bi * 16 * SST + tok * SST + which * 128 + part * 8;
;       *reinterpret_cast<float4*>(d) = make_float4(lo2f(st[x].x), hi2f(st[x].x), lo2f(st[x].y), hi2f(st[x].y));
;       *reinterpret_cast<float4*>(d + 4) = make_float4(lo2f(st[x].z), hi2f(st[x].z), lo2f(st[x].w), hi2f(st[x].w));
;     }
;     {
;       const int tok = tid >> 4, pp = tid & 15;
;       float* d = buf + bi * 16 * SST + tok * SST;
;       const float stx = bf2f(stxr);
;       d[256 + pp] = stx * stdt;
;       d[272 + pp] = stx;
;       if (pp == 0) d[288] = __expf(stdt * Ah);
;     }
;   };
;   half_barrier(smem);
;   gload(0);
;   lwrite(0);
;   half_barrier(smem);
.LBB0_534:
	s_or_b64 exec, exec, s[2:3]
	s_lshr_b32 s2, s11, 2
	s_lshl_b32 s2, s2, 6
	s_and_b32 s10, s57, 0x70
	s_and_b32 s4, s2, 0x80
	s_lshl_b32 s2, s11, 4
	s_bitset1_b32 s10, 14
	s_and_b32 s2, s2, 48
	s_lshl_b32 s3, s28, 7
	s_add_u32 s3, s44, s3
	s_addc_u32 s5, s45, 0
	s_lshl_b32 s29, s2, 1
	s_add_u32 s72, s3, s29
	s_waitcnt vmcnt(1)
	v_mul_f32_e32 v0, 0x3fb8aa3b, v0
	v_ashrrev_i32_e32 v47, 5, v12
	v_lshlrev_b32_e32 v2, 4, v12
	s_addc_u32 s73, s5, 0
	s_lshl_b32 s2, s28, 2
	v_exp_f32_e32 v46, v0
	v_add_u32_e32 v0, s10, v47
	v_mov_b64_e32 v[4:5], s[44:45]
	v_and_b32_e32 v2, 0x100, v2
	s_add_u32 s40, s88, s2
	v_mad_i64_i32 v[0:1], s[2:3], v0, s0, v[4:5]
	v_lshlrev_b32_e32 v148, 1, v2
	v_lshlrev_b32_e32 v13, 3, v12
	v_add_u32_e32 v6, 0x100, v12
	s_addc_u32 s41, s94, 0
	v_lshl_add_u64 v[0:1], v[0:1], 0, v[148:149]
	s_lshl_b32 s80, s4, 1
	v_and_b32_e32 v18, 0x78, v13
	v_ashrrev_i32_e32 v48, 5, v6
	v_lshl_add_u64 v[0:1], v[0:1], 0, s[80:81]
	v_lshlrev_b32_e32 v8, 1, v18
	v_mov_b32_e32 v9, v149
	v_add_u32_e32 v6, s10, v48
	v_lshl_add_u64 v[0:1], v[0:1], 0, v[8:9]
	v_mad_i64_i32 v[4:5], s[2:3], v6, s0, v[4:5]
	global_load_dwordx4 v[0:3], v[0:1], off offset:512
	v_lshl_add_u64 v[4:5], v[4:5], 0, v[148:149]
	v_lshl_add_u64 v[4:5], v[4:5], 0, s[80:81]
	v_ashrrev_i32_e32 v45, 4, v12
	v_lshl_add_u64 v[4:5], v[4:5], 0, v[8:9]
	v_and_b32_e32 v44, 15, v12
	global_load_dwordx4 v[4:7], v[4:5], off offset:512
	v_add_u32_e32 v14, s10, v45
	v_mov_b64_e32 v[10:11], s[72:73]
	v_mad_i64_i32 v[16:17], s[2:3], v14, s0, v[10:11]
	v_lshlrev_b32_e32 v10, 1, v44
	v_mov_b32_e32 v11, v149
	v_ashrrev_i32_e32 v15, 31, v14
	v_lshl_add_u64 v[16:17], v[16:17], 0, v[10:11]
	global_load_ushort v49, v[16:17], off
	v_lshl_add_u64 v[14:15], v[14:15], 4, s[40:41]
	global_load_dword v54, v[14:15], off
	s_movk_i32 s1, 0x128
	v_mul_lo_u32 v50, v47, s1
	v_and_b32_e32 v11, 0x80, v13
	v_lshl_add_u32 v9, v50, 2, s63
	v_lshlrev_b32_e32 v51, 2, v11
	v_lshlrev_b32_e32 v52, 2, v18
	v_add3_u32 v9, v9, v51, v52
	v_mul_lo_u32 v53, v48, s1
	v_mul_lo_u32 v55, v45, s1
	v_cmp_eq_u32_e64 s[38:39], 0, v44
	s_waitcnt vmcnt(3)
	v_lshlrev_b32_e32 v14, 16, v0
	v_and_b32_e32 v15, 0xffff0000, v0
	v_lshlrev_b32_e32 v16, 16, v1
	v_and_b32_e32 v17, 0xffff0000, v1
	ds_write_b128 v9, v[14:17]
	v_lshlrev_b32_e32 v14, 16, v2
	v_and_b32_e32 v15, 0xffff0000, v2
	v_lshlrev_b32_e32 v16, 16, v3
	v_and_b32_e32 v17, 0xffff0000, v3
	ds_write_b128 v9, v[14:17] offset:16
	v_lshl_add_u32 v9, v53, 2, s63
	v_add3_u32 v9, v9, v51, v52
	s_waitcnt vmcnt(2)
	v_lshlrev_b32_e32 v14, 16, v4
	v_and_b32_e32 v15, 0xffff0000, v4
	v_lshlrev_b32_e32 v16, 16, v5
	v_and_b32_e32 v17, 0xffff0000, v5
	ds_write_b128 v9, v[14:17]
	v_lshlrev_b32_e32 v14, 16, v6
	v_and_b32_e32 v15, 0xffff0000, v6
	v_lshlrev_b32_e32 v16, 16, v7
	v_and_b32_e32 v17, 0xffff0000, v7
	ds_write_b128 v9, v[14:17] offset:16
	v_lshl_add_u32 v9, v55, 2, s63
	s_waitcnt vmcnt(1)
	v_lshlrev_b32_e32 v11, 16, v49
	v_mul_u32_u24_e32 v83, 0x4a0, v44
	v_lshl_add_u32 v83, v45, 3, v83
	v_add_u32_e32 v83, 0x400, v83
	s_waitcnt vmcnt(0)
	v_mul_f32_e32 v13, v54, v11
	v_add_u32_e32 v14, s63, v83
	ds_write2_b32 v14, v13, v13 offset1:1
	v_lshlrev_b32_e32 v15, 6, v44
	v_lshl_add_u32 v15, v45, 2, v15
	v_add_u32_e32 v15, s63, v15
	ds_write_b32 v15, v11 offset:38912
	s_and_saveexec_b64 s[2:3], s[38:39]
	s_cbranch_execz .LBB0_536
	v_mul_f32_e32 v11, v54, v46
	v_mul_f32_e32 v11, 0xbfb8aa3b, v11
	v_exp_f32_e32 v11, v11
	v_lshl_add_u32 v9, v45, 3, s63
	v_add_u32_e32 v9, 0x9400, v9
	ds_write2_b32 v9, v11, v11 offset1:1

; __device__ __forceinline__ void ssd_scan_unit(CP p, int l, int u, char* smem) {
;     ...
;   half_barrier(smem);
;   gload(0);
;   lwrite(0);
;   half_barrier(smem);
;   constexpr int NCH = T / 16;
;   for (int c = 0; c < NCH; ++c) {
;     if (c + 1 < NCH) gload(c + 1);
;     const float* cb = buf + (c & 1) * 16 * SST;
;     float ykeep = 0.f;
;     float4 B0 = *reinterpret_cast<const float4*>(cb + j * 4), B1 = *reinterpret_cast<const float4*>(cb + 64 + j * 4);
;     float4 C0 = *reinterpret_cast<const float4*>(cb + 128 + j * 4), C1 = *reinterpret_cast<const float4*>(cb + 192 + j * 4);
;     float xdt = cb[256 + prow], xr = cb[272 + prow], a = cb[288];
; #pragma unroll 2
;     for (int s = 0; s < 16; ++s) {
;       const float* sb = cb + (s + 1) * SST;
;       const float4 B0n = *reinterpret_cast<const float4*>(sb + j * 4), B1n = *reinterpret_cast<const float4*>(sb + 64 + j * 4);
;       const float4 C0n = *reinterpret_cast<const float4*>(sb + 128 + j * 4), C1n = *reinterpret_cast<const float4*>(sb + 192 + j * 4);
;       const float xdtn = sb[256 + prow], xrn = sb[272 + prow], an = sb[288];
;       __builtin_amdgcn_sched_barrier(0);
;       hs[0] = fmaf(a, hs[0], xdt * B0.x); hs[1] = fmaf(a, hs[1], xdt * B0.y); hs[2] = fmaf(a, hs[2], xdt * B0.z); hs[3] = fmaf(a, hs[3], xdt * B0.w);
;       hs[4] = fmaf(a, hs[4], xdt * B1.x); hs[5] = fmaf(a, hs[5], xdt * B1.y); hs[6] = fmaf(a, hs[6], xdt * B1.z); hs[7] = fmaf(a, hs[7], xdt * B1.w);
;       float y = hs[0] * C0.x + hs[1] * C0.y + hs[2] * C0.z + hs[3] * C0.w + hs[4] * C1.x + hs[5] * C1.y + hs[6] * C1.z + hs[7] * C1.w;
;       y = allreduce16(y);
;       y = fmaf(Dh, xr, y);
;       if (j == s) ykeep = y;
;       B0 = B0n; B1 = B1n; C0 = C0n; C1 = C1n; xdt = xdtn; xr = xrn; a = an;
;     }
.LBB0_542:
	s_or_b64 exec, exec, s[2:3]
	s_lshl_b32 s3, s11, 7
	s_lshl_b32 s2, s28, 6
	s_and_b32 s11, s3, 0x3800
	s_add_i32 s11, s11, -16
	s_lshl_b32 s2, s2, 1
	v_readlane_b32 s4, v254, 7
	v_mov_b32_e32 v11, v149
	v_readlane_b32 s5, v254, 8
	s_add_u32 s2, s4, s2
	v_lshrrev_b32_e32 v9, 4, v12
	v_lshl_add_u64 v[26:27], s[72:73], 0, v[10:11]
	v_lshl_add_u64 v[10:11], s[44:45], 0, v[148:149]
	s_addc_u32 s3, s5, 0
	v_bfe_u32 v12, v12, 4, 2
	v_bfi_b32 v24, -4, v45, v9
	v_lshl_add_u64 v[10:11], v[10:11], 0, s[80:81]
	v_mov_b32_e32 v9, v149
	s_add_u32 s2, s2, s29
	v_lshl_add_u64 v[30:31], v[10:11], 0, v[8:9]
	v_lshlrev_b32_e32 v8, 2, v45
	v_lshlrev_b32_e32 v9, 2, v12
	s_addc_u32 s3, s3, 0
	v_ashrrev_i32_e32 v25, 31, v24
	v_and_or_b32 v8, v8, -16, v9
	v_mov_b32_e32 v32, 0
	v_lshlrev_b32_e32 v56, 2, v44
	v_lshl_add_u64 v[28:29], v[24:25], 1, s[2:3]
	v_add_u32_e32 v25, 0x8a0, v8
	v_lshlrev_b32_e32 v57, 4, v44
	s_mov_b32 s4, 0
	s_mov_b64 s[72:73], 0
	v_mov_b32_e32 v33, v32
	v_mov_b32_e32 v38, v32
	v_mov_b32_e32 v39, v32
	v_mov_b32_e32 v36, v32
	v_mov_b32_e32 v37, v32
	v_mov_b32_e32 v34, v32
	v_mov_b32_e32 v35, v32
	v_mov_b32_e32 v193, 0x20000
	v_lshl_add_u32 v193, v213, 2, v193
	v_mov_b32_e32 v195, 1
	ds_read_b32 v194, v193 offset:8
	v_mul_u32_u24_e32 v82, 0x4a0, v24
	v_lshlrev_b32_e32 v81, 6, v24
	v_lshl_add_u32 v81, v44, 2, v81
	v_lshlrev_b32_e32 v80, 6, v44
	v_lshl_add_u32 v80, v45, 2, v80
	s_add_i32 s5, s11, 16
	v_add_u32_e32 v8, s5, v45
	v_add_u32_e32 v0, s5, v47
	v_add_u32_e32 v4, s5, v48
	v_ashrrev_i32_e32 v9, 31, v8
	v_mad_i64_i32 v[0:1], s[12:13], v0, s0, v[30:31]
	v_mad_i64_i32 v[4:5], s[12:13], v4, s0, v[30:31]
	v_mad_i64_i32 v[10:11], s[12:13], v8, s0, v[26:27]
	v_lshl_add_u64 v[8:9], v[8:9], 4, s[40:41]
	global_load_dwordx4 v[0:3], v[0:1], off offset:512
	global_load_dwordx4 v[4:7], v[4:5], off offset:512
	global_load_ushort v49, v[10:11], off
	global_load_dword v54, v[8:9], off
	s_waitcnt lgkmcnt(0)
	v_and_b32_e32 v194, -4, v194
.Lsd_head:
	s_add_i32 s28, s4, 1
	s_bitcmp1_b32 s4, 0
	s_cselect_b32 s12, 0x4a00, 0
	s_cselect_b32 s13, 0x80, 0
	s_cselect_b32 s5, 0x400, 0
	s_add_i32 s12, s63, s12
	s_add_i32 s13, s63, s13
	s_add_i32 s5, s63, s5
	v_lshl_add_u32 v84, v56, 2, s12
	v_add_u32_e32 v85, s12, v82
	v_mov_b32_e32 v86, s13
	v_add_u32_e32 v87, s5, v81
	ds_read_b128 v[106:109], v85 offset:1024
	ds_read_b128 v[134:137], v86 offset:37888
	ds_read_b128 v[128:131], v85 offset:1040
	ds_read_b128 v[138:141], v86 offset:37904
	ds_read_b128 v[90:93], v84 offset:0
	ds_read_b128 v[94:97], v84 offset:256
	ds_read_b128 v[98:101], v84 offset:512
	ds_read_b128 v[102:105], v84 offset:768
	ds_read_b128 v[112:115], v84 offset:1184
	ds_read_b128 v[116:119], v84 offset:1440
	ds_read_b128 v[120:123], v84 offset:1696
	ds_read_b128 v[124:127], v84 offset:1952
	ds_read_b32 v186, v87 offset:38912
	s_waitcnt lgkmcnt(7)
	v_pk_mul_f32 v[176:177], v[90:91], v[106:107]
	v_pk_mul_f32 v[178:179], v[92:93], v[106:107]
	v_pk_mul_f32 v[180:181], v[94:95], v[106:107]
	v_pk_mul_f32 v[182:183], v[96:97], v[106:107]
	ds_read_b128 v[90:93], v84 offset:2368
	ds_read_b128 v[94:97], v84 offset:2624
	s_waitcnt lgkmcnt(5)
	v_pk_fma_f32 v[32:33], v[134:135], v[32:33], v[176:177]
	v_pk_fma_f32 v[38:39], v[134:135], v[38:39], v[178:179]
	v_pk_fma_f32 v[36:37], v[134:135], v[36:37], v[180:181]
	v_pk_fma_f32 v[34:35], v[134:135], v[34:35], v[182:183]
	v_pk_mul_f32 v[184:185], v[32:33], v[98:99]
	v_pk_mul_f32 v[176:177], v[112:113], v[108:109]
	v_pk_fma_f32 v[184:185], v[38:39], v[100:101], v[184:185]
	v_pk_mul_f32 v[178:179], v[114:115], v[108:109]
	v_pk_fma_f32 v[184:185], v[36:37], v[102:103], v[184:185]
	v_pk_mul_f32 v[180:181], v[116:117], v[108:109]
	v_pk_fma_f32 v[184:185], v[34:35], v[104:105], v[184:185]
	v_pk_mul_f32 v[182:183], v[118:119], v[108:109]
	v_add_f32_e32 v160, v184, v185
	ds_read_b128 v[112:115], v84 offset:3552
	ds_read_b128 v[116:119], v84 offset:3808
	ds_read_b128 v[98:101], v84 offset:2880
	ds_read_b128 v[102:105], v84 offset:3136
	ds_read_b128 v[106:109], v85 offset:1056
	s_waitcnt lgkmcnt(5)
	v_pk_fma_f32 v[32:33], v[136:137], v[32:33], v[176:177]
	v_pk_fma_f32 v[38:39], v[136:137], v[38:39], v[178:179]
	v_pk_fma_f32 v[36:37], v[136:137], v[36:37], v[180:181]
	v_pk_fma_f32 v[34:35], v[136:137], v[34:35], v[182:183]
	v_pk_mul_f32 v[184:185], v[32:33], v[120:121]
	v_pk_mul_f32 v[176:177], v[90:91], v[128:129]
	v_pk_fma_f32 v[184:185], v[38:39], v[122:123], v[184:185]
	v_pk_mul_f32 v[178:179], v[92:93], v[128:129]
	v_pk_fma_f32 v[184:185], v[36:37], v[124:125], v[184:185]
	v_pk_mul_f32 v[180:181], v[94:95], v[128:129]
	v_pk_fma_f32 v[184:185], v[34:35], v[126:127], v[184:185]
	v_pk_mul_f32 v[182:183], v[96:97], v[128:129]
	v_add_f32_e32 v161, v184, v185
	ds_read_b128 v[90:93], v84 offset:4736
	ds_read_b128 v[94:97], v84 offset:4992
	ds_read_b128 v[120:123], v84 offset:4064
	ds_read_b128 v[124:127], v84 offset:4320
	ds_read_b128 v[134:137], v86 offset:37920
	s_waitcnt lgkmcnt(6)
	v_pk_fma_f32 v[32:33], v[138:139], v[32:33], v[176:177]
	v_pk_fma_f32 v[38:39], v[138:139], v[38:39], v[178:179]
	v_pk_fma_f32 v[36:37], v[138:139], v[36:37], v[180:181]
	v_pk_fma_f32 v[34:35], v[138:139], v[34:35], v[182:183]
	v_pk_mul_f32 v[184:185], v[32:33], v[98:99]
	v_pk_mul_f32 v[176:177], v[112:113], v[130:131]
	v_pk_fma_f32 v[184:185], v[38:39], v[100:101], v[184:185]
	v_pk_mul_f32 v[178:179], v[114:115], v[130:131]
	v_pk_fma_f32 v[184:185], v[36:37], v[102:103], v[184:185]
	v_pk_mul_f32 v[180:181], v[116:117], v[130:131]
	v_pk_fma_f32 v[184:185], v[34:35], v[104:105], v[184:185]
	v_pk_mul_f32 v[182:183], v[118:119], v[130:131]
	v_add_f32_e32 v162, v184, v185
	ds_read_b128 v[112:115], v84 offset:5920
	ds_read_b128 v[116:119], v84 offset:6176
	ds_read_b128 v[98:101], v84 offset:5248
	ds_read_b128 v[102:105], v84 offset:5504
	ds_read_b128 v[128:131], v85 offset:1072
	s_waitcnt lgkmcnt(6)
; __device__ __forceinline__ void ssd_scan_unit(CP p, int l, int u, char* smem) {
;     ...
;   auto gload = [&](int c) {
;     const int rb = rowof(b, c * 16);
; #pragma unroll
;     for (int x = 0; x < 2; ++x) {
;       const int e = tid + x * 256, tok = e >> 5, rem = e & 31, which = rem >> 4, part = rem & 15;
;       st[x] = *reinterpret_cast<const uint4*>(SS + (size_t)(rb + tok) * 768 + 256 + which * 256 + g * 128 + part * 8);
;     }
;     {
;       const int tok = tid >> 4, pp = tid & 15;
;       stxr = SS[(size_t)(rb + tok) * 768 + h * 64 + q * 16 + pp];
;       stdt = SD[(size_t)(rb + tok) * 4 + h];
;     }
;   };
;   auto lwrite = [&](int bi) {
; #pragma unroll
;     for (int x = 0; x < 2; ++x) {
;       const int e = tid + x * 256, tok = e >> 5, rem = e & 31, which = rem >> 4, part = rem & 15;
;       float* d = buf + bi * 16 * SST + tok * SST + which * 128 + part * 8;
;       *reinterpret_cast<float4*>(d) = make_float4(lo2f(st[x].x), hi2f(st[x].x), lo2f(st[x].y), hi2f(st[x].y));
;       *reinterpret_cast<float4*>(d + 4) = make_float4(lo2f(st[x].z), hi2f(st[x].z), lo2f(st[x].w), hi2f(st[x].w));
;     }
;     {
;       const int tok = tid >> 4, pp = tid & 15;
;       float* d = buf + bi * 16 * SST + tok * SST;
;       const float stx = bf2f(stxr);
;       d[256 + pp] = stx * stdt;
;     ...
;     for (int s = 0; s < 16; ++s) {
;       const float* sb = cb + (s + 1) * SST;
;       const float4 B0n = *reinterpret_cast<const float4*>(sb + j * 4), B1n = *reinterpret_cast<const float4*>(sb + 64 + j * 4);
;       const float4 C0n = *reinterpret_cast<const float4*>(sb + 128 + j * 4), C1n = *reinterpret_cast<const float4*>(sb + 192 + j * 4);
;       const float xdtn = sb[256 + prow], xrn = sb[272 + prow], an = sb[288];
;       __builtin_amdgcn_sched_barrier(0);
;       hs[0] = fmaf(a, hs[0], xdt * B0.x); hs[1] = fmaf(a, hs[1], xdt * B0.y); hs[2] = fmaf(a, hs[2], xdt * B0.z); hs[3] = fmaf(a, hs[3], xdt * B0.w);
;       hs[4] = fmaf(a, hs[4], xdt * B1.x); hs[5] = fmaf(a, hs[5], xdt * B1.y); hs[6] = fmaf(a, hs[6], xdt * B1.z); hs[7] = fmaf(a, hs[7], xdt * B1.w);
;       float y = hs[0] * C0.x + hs[1] * C0.y + hs[2] * C0.z + hs[3] * C0.w + hs[4] * C1.x + hs[5] * C1.y + hs[6] * C1.z + hs[7] * C1.w;
;       y = allreduce16(y);
;       y = fmaf(Dh, xr, y);
;       if (j == s) ykeep = y;
;       B0 = B0n; B1 = B1n; C0 = C0n; C1 = C1n; xdt = xdtn; xr = xrn; a = an;
;     }
	v_pk_fma_f32 v[32:33], v[140:141], v[32:33], v[176:177]
	v_pk_fma_f32 v[38:39], v[140:141], v[38:39], v[178:179]
	v_pk_fma_f32 v[36:37], v[140:141], v[36:37], v[180:181]
	v_pk_fma_f32 v[34:35], v[140:141], v[34:35], v[182:183]
	v_pk_mul_f32 v[184:185], v[32:33], v[120:121]
	v_pk_mul_f32 v[176:177], v[90:91], v[106:107]
	v_pk_fma_f32 v[184:185], v[38:39], v[122:123], v[184:185]
	v_pk_mul_f32 v[178:179], v[92:93], v[106:107]
	v_pk_fma_f32 v[184:185], v[36:37], v[124:125], v[184:185]
	v_pk_mul_f32 v[180:181], v[94:95], v[106:107]
	v_pk_fma_f32 v[184:185], v[34:35], v[126:127], v[184:185]
	v_pk_mul_f32 v[182:183], v[96:97], v[106:107]
	v_add_f32_e32 v163, v184, v185
	ds_read_b128 v[90:93], v84 offset:7104
	ds_read_b128 v[94:97], v84 offset:7360
	ds_read_b128 v[120:123], v84 offset:6432
	ds_read_b128 v[124:127], v84 offset:6688
	ds_read_b128 v[138:141], v86 offset:37936
	s_waitcnt lgkmcnt(6)
	v_pk_fma_f32 v[32:33], v[134:135], v[32:33], v[176:177]
	v_pk_fma_f32 v[38:39], v[134:135], v[38:39], v[178:179]
	v_pk_fma_f32 v[36:37], v[134:135], v[36:37], v[180:181]
	v_pk_fma_f32 v[34:35], v[134:135], v[34:35], v[182:183]
	v_pk_mul_f32 v[184:185], v[32:33], v[98:99]
	v_pk_mul_f32 v[176:177], v[112:113], v[108:109]
	v_pk_fma_f32 v[184:185], v[38:39], v[100:101], v[184:185]
	v_pk_mul_f32 v[178:179], v[114:115], v[108:109]
	v_pk_fma_f32 v[184:185], v[36:37], v[102:103], v[184:185]
	v_pk_mul_f32 v[180:181], v[116:117], v[108:109]
	v_pk_fma_f32 v[184:185], v[34:35], v[104:105], v[184:185]
	v_pk_mul_f32 v[182:183], v[118:119], v[108:109]
	v_add_f32_e32 v164, v184, v185
	ds_read_b128 v[112:115], v84 offset:8288
	ds_read_b128 v[116:119], v84 offset:8544
	ds_read_b128 v[98:101], v84 offset:7616
	ds_read_b128 v[102:105], v84 offset:7872
	ds_read_b128 v[106:109], v85 offset:1088
	s_waitcnt lgkmcnt(6)
	v_pk_fma_f32 v[32:33], v[136:137], v[32:33], v[176:177]
	v_pk_fma_f32 v[38:39], v[136:137], v[38:39], v[178:179]
	v_pk_fma_f32 v[36:37], v[136:137], v[36:37], v[180:181]
	v_pk_fma_f32 v[34:35], v[136:137], v[34:35], v[182:183]
	v_pk_mul_f32 v[184:185], v[32:33], v[120:121]
	v_pk_mul_f32 v[176:177], v[90:91], v[128:129]
	v_pk_fma_f32 v[184:185], v[38:39], v[122:123], v[184:185]
	v_pk_mul_f32 v[178:179], v[92:93], v[128:129]
	v_pk_fma_f32 v[184:185], v[36:37], v[124:125], v[184:185]
	v_pk_mul_f32 v[180:181], v[94:95], v[128:129]
	v_pk_fma_f32 v[184:185], v[34:35], v[126:127], v[184:185]
	v_pk_mul_f32 v[182:183], v[96:97], v[128:129]
	v_add_f32_e32 v165, v184, v185
	ds_read_b128 v[90:93], v84 offset:9472
	ds_read_b128 v[94:97], v84 offset:9728
	ds_read_b128 v[120:123], v84 offset:8800
	ds_read_b128 v[124:127], v84 offset:9056
	ds_read_b128 v[134:137], v86 offset:37952
	s_waitcnt lgkmcnt(6)
	v_pk_fma_f32 v[32:33], v[138:139], v[32:33], v[176:177]
	v_pk_fma_f32 v[38:39], v[138:139], v[38:39], v[178:179]
	v_pk_fma_f32 v[36:37], v[138:139], v[36:37], v[180:181]
	v_pk_fma_f32 v[34:35], v[138:139], v[34:35], v[182:183]
	v_pk_mul_f32 v[184:185], v[32:33], v[98:99]
	v_pk_mul_f32 v[176:177], v[112:113], v[130:131]
	v_pk_fma_f32 v[184:185], v[38:39], v[100:101], v[184:185]
	v_pk_mul_f32 v[178:179], v[114:115], v[130:131]
	v_pk_fma_f32 v[184:185], v[36:37], v[102:103], v[184:185]
	v_pk_mul_f32 v[180:181], v[116:117], v[130:131]
	v_pk_fma_f32 v[184:185], v[34:35], v[104:105], v[184:185]
	v_pk_mul_f32 v[182:183], v[118:119], v[130:131]
	v_add_f32_e32 v166, v184, v185
	ds_read_b128 v[112:115], v84 offset:10656
	ds_read_b128 v[116:119], v84 offset:10912
	ds_read_b128 v[98:101], v84 offset:9984
	ds_read_b128 v[102:105], v84 offset:10240
	ds_read_b128 v[128:131], v85 offset:1104
	s_waitcnt lgkmcnt(6)
	v_pk_fma_f32 v[32:33], v[140:141], v[32:33], v[176:177]
	v_pk_fma_f32 v[38:39], v[140:141], v[38:39], v[178:179]
	v_pk_fma_f32 v[36:37], v[140:141], v[36:37], v[180:181]
	v_pk_fma_f32 v[34:35], v[140:141], v[34:35], v[182:183]
	v_pk_mul_f32 v[184:185], v[32:33], v[120:121]
	v_pk_mul_f32 v[176:177], v[90:91], v[106:107]
	v_pk_fma_f32 v[184:185], v[38:39], v[122:123], v[184:185]
	v_pk_mul_f32 v[178:179], v[92:93], v[106:107]
	v_pk_fma_f32 v[184:185], v[36:37], v[124:125], v[184:185]
	v_pk_mul_f32 v[180:181], v[94:95], v[106:107]
	v_pk_fma_f32 v[184:185], v[34:35], v[126:127], v[184:185]
	v_pk_mul_f32 v[182:183], v[96:97], v[106:107]
	v_add_f32_e32 v167, v184, v185
	ds_read_b128 v[90:93], v84 offset:11840
	ds_read_b128 v[94:97], v84 offset:12096
	ds_read_b128 v[120:123], v84 offset:11168
	ds_read_b128 v[124:127], v84 offset:11424
	ds_read_b128 v[138:141], v86 offset:37968
	s_waitcnt vmcnt(0)
	s_bitcmp1_b32 s28, 0
	s_cselect_b32 s2, 0x4a00, 0
	s_cselect_b32 s5, 0x80, 0
	s_add_i32 s2, s63, s2
	v_lshl_add_u32 v8, v50, 2, s2
	v_add3_u32 v18, v8, v51, v52
	v_lshlrev_b32_e32 v12, 16, v0
	v_and_b32_e32 v13, 0xffff0000, v0
	v_lshlrev_b32_e32 v14, 16, v1
	v_and_b32_e32 v15, 0xffff0000, v1
	ds_write_b128 v18, v[12:15]
	v_lshlrev_b32_e32 v12, 16, v2
	v_and_b32_e32 v13, 0xffff0000, v2
	v_lshlrev_b32_e32 v14, 16, v3
	v_and_b32_e32 v15, 0xffff0000, v3
	ds_write_b128 v18, v[12:15] offset:16
	v_lshl_add_u32 v8, v53, 2, s2
	v_add3_u32 v18, v8, v51, v52
	v_lshlrev_b32_e32 v12, 16, v4
	v_and_b32_e32 v13, 0xffff0000, v4
	v_lshlrev_b32_e32 v14, 16, v5
	v_and_b32_e32 v15, 0xffff0000, v5
	ds_write_b128 v18, v[12:15]
	v_lshlrev_b32_e32 v12, 16, v6
	v_and_b32_e32 v13, 0xffff0000, v6
	v_lshlrev_b32_e32 v14, 16, v7
	v_and_b32_e32 v15, 0xffff0000, v7
	ds_write_b128 v18, v[12:15] offset:16
	v_lshlrev_b32_e32 v9, 16, v49
	v_mul_f32_e32 v10, v54, v9
	v_add_u32_e32 v11, s2, v83
	ds_write2_b32 v11, v10, v10 offset1:1
	s_bitcmp1_b32 s28, 0
	s_cselect_b32 s12, 0x400, 0
	s_add_i32 s12, s63, s12
	v_add_u32_e32 v11, s12, v80
	ds_write_b32 v11, v9 offset:38912
	v_mul_f32_e32 v9, v54, v46
	v_mul_f32_e32 v9, 0xbfb8aa3b, v9
	v_exp_f32_e32 v9, v9
	v_lshl_add_u32 v8, v45, 3, s63
	v_add_u32_e32 v8, s5, v8
	v_add_u32_e32 v8, 0x9400, v8
	ds_write2_b32 v8, v9, v9 offset1:1
	s_cmpk_gt_i32 s4, 0x7e
	s_cbranch_scc1 .Lsd_skipgl
	s_add_i32 s5, s4, 2
	s_lshl_b32 s5, s5, 4
	s_add_i32 s5, s5, s11
	v_add_u32_e32 v8, s5, v45
	v_add_u32_e32 v0, s5, v47
	v_add_u32_e32 v4, s5, v48
	v_ashrrev_i32_e32 v9, 31, v8
	v_mad_i64_i32 v[0:1], s[12:13], v0, s0, v[30:31]
	v_mad_i64_i32 v[4:5], s[12:13], v4, s0, v[30:31]
	v_mad_i64_i32 v[10:11], s[12:13], v8, s0, v[26:27]
	v_lshl_add_u64 v[8:9], v[8:9], 4, s[40:41]
	global_load_dwordx4 v[0:3], v[0:1], off offset:512
	global_load_dwordx4 v[4:7], v[4:5], off offset:512
	global_load_ushort v49, v[10:11], off
	global_load_dword v54, v[8:9], off
; __device__ __forceinline__ void ssd_scan_unit(CP p, int l, int u, char* smem) {
;     ...
;     for (int s = 0; s < 16; ++s) {
;       const float* sb = cb + (s + 1) * SST;
;       const float4 B0n = *reinterpret_cast<const float4*>(sb + j * 4), B1n = *reinterpret_cast<const float4*>(sb + 64 + j * 4);
;       const float4 C0n = *reinterpret_cast<const float4*>(sb + 128 + j * 4), C1n = *reinterpret_cast<const float4*>(sb + 192 + j * 4);
;       const float xdtn = sb[256 + prow], xrn = sb[272 + prow], an = sb[288];
;       __builtin_amdgcn_sched_barrier(0);
;       hs[0] = fmaf(a, hs[0], xdt * B0.x); hs[1] = fmaf(a, hs[1], xdt * B0.y); hs[2] = fmaf(a, hs[2], xdt * B0.z); hs[3] = fmaf(a, hs[3], xdt * B0.w);
;       hs[4] = fmaf(a, hs[4], xdt * B1.x); hs[5] = fmaf(a, hs[5], xdt * B1.y); hs[6] = fmaf(a, hs[6], xdt * B1.z); hs[7] = fmaf(a, hs[7], xdt * B1.w);
;       float y = hs[0] * C0.x + hs[1] * C0.y + hs[2] * C0.z + hs[3] * C0.w + hs[4] * C1.x + hs[5] * C1.y + hs[6] * C1.z + hs[7] * C1.w;
;       y = allreduce16(y);
;       y = fmaf(Dh, xr, y);
;       if (j == s) ykeep = y;
;       B0 = B0n; B1 = B1n; C0 = C0n; C1 = C1n; xdt = xdtn; xr = xrn; a = an;
;     }
.Lsd_skipgl:
	s_waitcnt lgkmcnt(13)
	v_pk_fma_f32 v[32:33], v[134:135], v[32:33], v[176:177]
	v_pk_fma_f32 v[38:39], v[134:135], v[38:39], v[178:179]
	v_pk_fma_f32 v[36:37], v[134:135], v[36:37], v[180:181]
	v_pk_fma_f32 v[34:35], v[134:135], v[34:35], v[182:183]
	v_pk_mul_f32 v[184:185], v[32:33], v[98:99]
	v_pk_mul_f32 v[176:177], v[112:113], v[108:109]
	v_pk_fma_f32 v[184:185], v[38:39], v[100:101], v[184:185]
	v_pk_mul_f32 v[178:179], v[114:115], v[108:109]
	v_pk_fma_f32 v[184:185], v[36:37], v[102:103], v[184:185]
	v_pk_mul_f32 v[180:181], v[116:117], v[108:109]
	v_pk_fma_f32 v[184:185], v[34:35], v[104:105], v[184:185]
	v_pk_mul_f32 v[182:183], v[118:119], v[108:109]
	v_add_f32_e32 v168, v184, v185
	ds_read_b128 v[112:115], v84 offset:13024
	ds_read_b128 v[116:119], v84 offset:13280
	ds_read_b128 v[98:101], v84 offset:12352
	ds_read_b128 v[102:105], v84 offset:12608
	ds_read_b128 v[106:109], v85 offset:1120
	s_waitcnt lgkmcnt(13)
	v_pk_fma_f32 v[32:33], v[136:137], v[32:33], v[176:177]
	v_pk_fma_f32 v[38:39], v[136:137], v[38:39], v[178:179]
	v_pk_fma_f32 v[36:37], v[136:137], v[36:37], v[180:181]
	v_pk_fma_f32 v[34:35], v[136:137], v[34:35], v[182:183]
	v_pk_mul_f32 v[184:185], v[32:33], v[120:121]
	v_pk_mul_f32 v[176:177], v[90:91], v[128:129]
	v_pk_fma_f32 v[184:185], v[38:39], v[122:123], v[184:185]
	v_pk_mul_f32 v[178:179], v[92:93], v[128:129]
	v_pk_fma_f32 v[184:185], v[36:37], v[124:125], v[184:185]
	v_pk_mul_f32 v[180:181], v[94:95], v[128:129]
	v_pk_fma_f32 v[184:185], v[34:35], v[126:127], v[184:185]
	v_pk_mul_f32 v[182:183], v[96:97], v[128:129]
	v_add_f32_e32 v169, v184, v185
	ds_read_b128 v[90:93], v84 offset:14208
	ds_read_b128 v[94:97], v84 offset:14464
	ds_read_b128 v[120:123], v84 offset:13536
	ds_read_b128 v[124:127], v84 offset:13792
	ds_read_b128 v[134:137], v86 offset:37984
	s_waitcnt lgkmcnt(6)
	v_pk_fma_f32 v[32:33], v[138:139], v[32:33], v[176:177]
	v_pk_fma_f32 v[38:39], v[138:139], v[38:39], v[178:179]
	v_pk_fma_f32 v[36:37], v[138:139], v[36:37], v[180:181]
	v_pk_fma_f32 v[34:35], v[138:139], v[34:35], v[182:183]
	v_pk_mul_f32 v[184:185], v[32:33], v[98:99]
	v_pk_mul_f32 v[176:177], v[112:113], v[130:131]
	v_pk_fma_f32 v[184:185], v[38:39], v[100:101], v[184:185]
	v_pk_mul_f32 v[178:179], v[114:115], v[130:131]
	v_pk_fma_f32 v[184:185], v[36:37], v[102:103], v[184:185]
	v_pk_mul_f32 v[180:181], v[116:117], v[130:131]
	v_pk_fma_f32 v[184:185], v[34:35], v[104:105], v[184:185]
	v_pk_mul_f32 v[182:183], v[118:119], v[130:131]
	v_add_f32_e32 v170, v184, v185
	ds_read_b128 v[112:115], v84 offset:15392
	ds_read_b128 v[116:119], v84 offset:15648
	ds_read_b128 v[98:101], v84 offset:14720
	ds_read_b128 v[102:105], v84 offset:14976
	ds_read_b128 v[128:131], v85 offset:1136
	s_waitcnt lgkmcnt(6)
	v_pk_fma_f32 v[32:33], v[140:141], v[32:33], v[176:177]
	v_pk_fma_f32 v[38:39], v[140:141], v[38:39], v[178:179]
	v_pk_fma_f32 v[36:37], v[140:141], v[36:37], v[180:181]
	v_pk_fma_f32 v[34:35], v[140:141], v[34:35], v[182:183]
	v_pk_mul_f32 v[184:185], v[32:33], v[120:121]
	v_pk_mul_f32 v[176:177], v[90:91], v[106:107]
	v_pk_fma_f32 v[184:185], v[38:39], v[122:123], v[184:185]
	v_pk_mul_f32 v[178:179], v[92:93], v[106:107]
	v_pk_fma_f32 v[184:185], v[36:37], v[124:125], v[184:185]
	v_pk_mul_f32 v[180:181], v[94:95], v[106:107]
	v_pk_fma_f32 v[184:185], v[34:35], v[126:127], v[184:185]
	v_pk_mul_f32 v[182:183], v[96:97], v[106:107]
	v_add_f32_e32 v171, v184, v185
	ds_read_b128 v[90:93], v84 offset:16576
	ds_read_b128 v[94:97], v84 offset:16832
	ds_read_b128 v[120:123], v84 offset:15904
	ds_read_b128 v[124:127], v84 offset:16160
	ds_read_b128 v[138:141], v86 offset:38000
	s_waitcnt lgkmcnt(6)
	v_pk_fma_f32 v[32:33], v[134:135], v[32:33], v[176:177]
	v_pk_fma_f32 v[38:39], v[134:135], v[38:39], v[178:179]
	v_pk_fma_f32 v[36:37], v[134:135], v[36:37], v[180:181]
	v_pk_fma_f32 v[34:35], v[134:135], v[34:35], v[182:183]
	v_pk_mul_f32 v[184:185], v[32:33], v[98:99]
	v_pk_mul_f32 v[176:177], v[112:113], v[108:109]
	v_pk_fma_f32 v[184:185], v[38:39], v[100:101], v[184:185]
	v_pk_mul_f32 v[178:179], v[114:115], v[108:109]
	v_pk_fma_f32 v[184:185], v[36:37], v[102:103], v[184:185]
	v_pk_mul_f32 v[180:181], v[116:117], v[108:109]
	v_pk_fma_f32 v[184:185], v[34:35], v[104:105], v[184:185]
	v_pk_mul_f32 v[182:183], v[118:119], v[108:109]
	v_add_f32_e32 v172, v184, v185
	ds_read_b128 v[112:115], v84 offset:17760
	ds_read_b128 v[116:119], v84 offset:18016
	ds_read_b128 v[98:101], v84 offset:17088
	ds_read_b128 v[102:105], v84 offset:17344
	s_waitcnt lgkmcnt(5)
; __device__ __forceinline__ bf16_t f2bf(float f) { return (bf16_t)(pack2(f, 0.f) & 0xffffu); }
; __device__ __forceinline__ int tidx() { int t = threadIdx.x & 255; asm volatile("" : "+v"(t)); return t; }
; __device__ __forceinline__ int half_id() { int t = (int)(threadIdx.x >> 8); asm volatile("" : "+v"(t)); return __builtin_amdgcn_readfirstlane(t); }
; #define LAS3 __attribute__((address_space(3)))
; __device__ __forceinline__ void half_barrier(char* smem_half) {
;   const int h = half_id();
;   LAS3 unsigned* cnt = (LAS3 unsigned*)(smem_half + (2 - h) * 65536 + 8 + h * 4);
;   asm volatile("s_waitcnt lgkmcnt(0)" ::: "memory");
;   if ((tidx() & 63) == 0) {
;     const unsigned old = __hip_atomic_fetch_add(cnt, 1u, __ATOMIC_RELAXED, __HIP_MEMORY_SCOPE_WORKGROUP);
;     const unsigned target = (old & ~3u) + 4u;
;     while (__hip_atomic_load(cnt, __ATOMIC_RELAXED, __HIP_MEMORY_SCOPE_WORKGROUP) < target) __builtin_amdgcn_s_sleep(1);
;   }
; __device__ __forceinline__ void ssd_scan_unit(CP p, int l, int u, char* smem) {
;     ...
;     for (int s = 0; s < 16; ++s) {
;       const float* sb = cb + (s + 1) * SST;
;       const float4 B0n = *reinterpret_cast<const float4*>(sb + j * 4), B1n = *reinterpret_cast<const float4*>(sb + 64 + j * 4);
;       const float4 C0n = *reinterpret_cast<const float4*>(sb + 128 + j * 4), C1n = *reinterpret_cast<const float4*>(sb + 192 + j * 4);
;       const float xdtn = sb[256 + prow], xrn = sb[272 + prow], an = sb[288];
;       __builtin_amdgcn_sched_barrier(0);
;       hs[0] = fmaf(a, hs[0], xdt * B0.x); hs[1] = fmaf(a, hs[1], xdt * B0.y); hs[2] = fmaf(a, hs[2], xdt * B0.z); hs[3] = fmaf(a, hs[3], xdt * B0.w);
;       hs[4] = fmaf(a, hs[4], xdt * B1.x); hs[5] = fmaf(a, hs[5], xdt * B1.y); hs[6] = fmaf(a, hs[6], xdt * B1.z); hs[7] = fmaf(a, hs[7], xdt * B1.w);
;       float y = hs[0] * C0.x + hs[1] * C0.y + hs[2] * C0.z + hs[3] * C0.w + hs[4] * C1.x + hs[5] * C1.y + hs[6] * C1.z + hs[7] * C1.w;
;       y = allreduce16(y);
;       y = fmaf(Dh, xr, y);
;       if (j == s) ykeep = y;
;       B0 = B0n; B1 = B1n; C0 = C0n; C1 = C1n; xdt = xdtn; xr = xrn; a = an;
;     }
;     Y[(size_t)(rowof(b, c * 16) + j) * 1024 + h * 64 + q * 16 + prow] = f2bf(ykeep);
;     if (c + 1 < NCH) lwrite((c + 1) & 1);
;     half_barrier(smem);
	v_pk_fma_f32 v[32:33], v[136:137], v[32:33], v[176:177]
	v_pk_fma_f32 v[38:39], v[136:137], v[38:39], v[178:179]
	v_pk_fma_f32 v[36:37], v[136:137], v[36:37], v[180:181]
	v_pk_fma_f32 v[34:35], v[136:137], v[34:35], v[182:183]
	v_pk_mul_f32 v[184:185], v[32:33], v[120:121]
	v_pk_mul_f32 v[176:177], v[90:91], v[128:129]
	v_pk_fma_f32 v[184:185], v[38:39], v[122:123], v[184:185]
	v_pk_mul_f32 v[178:179], v[92:93], v[128:129]
	v_pk_fma_f32 v[184:185], v[36:37], v[124:125], v[184:185]
	v_pk_mul_f32 v[180:181], v[94:95], v[128:129]
	v_pk_fma_f32 v[184:185], v[34:35], v[126:127], v[184:185]
	v_pk_mul_f32 v[182:183], v[96:97], v[128:129]
	v_add_f32_e32 v173, v184, v185
	ds_read_b128 v[120:123], v84 offset:18272
	ds_read_b128 v[124:127], v84 offset:18528
	s_waitcnt lgkmcnt(2)
	v_pk_fma_f32 v[32:33], v[138:139], v[32:33], v[176:177]
	v_pk_fma_f32 v[38:39], v[138:139], v[38:39], v[178:179]
	v_pk_fma_f32 v[36:37], v[138:139], v[36:37], v[180:181]
	v_pk_fma_f32 v[34:35], v[138:139], v[34:35], v[182:183]
	v_pk_mul_f32 v[184:185], v[32:33], v[98:99]
	v_pk_mul_f32 v[176:177], v[112:113], v[130:131]
	v_pk_fma_f32 v[184:185], v[38:39], v[100:101], v[184:185]
	v_pk_mul_f32 v[178:179], v[114:115], v[130:131]
	v_pk_fma_f32 v[184:185], v[36:37], v[102:103], v[184:185]
	v_pk_mul_f32 v[180:181], v[116:117], v[130:131]
	v_pk_fma_f32 v[184:185], v[34:35], v[104:105], v[184:185]
	v_pk_mul_f32 v[182:183], v[118:119], v[130:131]
	v_add_f32_e32 v174, v184, v185
	s_waitcnt lgkmcnt(0)
	v_pk_fma_f32 v[32:33], v[140:141], v[32:33], v[176:177]
	v_pk_fma_f32 v[38:39], v[140:141], v[38:39], v[178:179]
	v_pk_fma_f32 v[36:37], v[140:141], v[36:37], v[180:181]
	v_pk_fma_f32 v[34:35], v[140:141], v[34:35], v[182:183]
	v_pk_mul_f32 v[184:185], v[32:33], v[120:121]
	v_pk_fma_f32 v[184:185], v[38:39], v[122:123], v[184:185]
	v_pk_fma_f32 v[184:185], v[36:37], v[124:125], v[184:185]
	v_pk_fma_f32 v[184:185], v[34:35], v[126:127], v[184:185]
	v_add_f32_e32 v175, v184, v185
	v_add_f32_dpp v160, v160, v160 row_ror:8 row_mask:0xf bank_mask:0x3 bound_ctrl:1
	v_add_f32_dpp v161, v161, v161 row_ror:8 row_mask:0xf bank_mask:0x3 bound_ctrl:1
	v_add_f32_dpp v162, v162, v162 row_ror:8 row_mask:0xf bank_mask:0x3 bound_ctrl:1
	v_add_f32_dpp v163, v163, v163 row_ror:8 row_mask:0xf bank_mask:0x3 bound_ctrl:1
	v_add_f32_dpp v164, v164, v164 row_ror:8 row_mask:0xf bank_mask:0x3 bound_ctrl:1
	v_add_f32_dpp v165, v165, v165 row_ror:8 row_mask:0xf bank_mask:0x3 bound_ctrl:1
	v_add_f32_dpp v166, v166, v166 row_ror:8 row_mask:0xf bank_mask:0x3 bound_ctrl:1
	v_add_f32_dpp v167, v167, v167 row_ror:8 row_mask:0xf bank_mask:0x3 bound_ctrl:1
	v_add_f32_dpp v160, v168, v168 row_ror:8 row_mask:0xf bank_mask:0xc bound_ctrl:1
	v_add_f32_dpp v161, v169, v169 row_ror:8 row_mask:0xf bank_mask:0xc bound_ctrl:1
	v_add_f32_dpp v162, v170, v170 row_ror:8 row_mask:0xf bank_mask:0xc bound_ctrl:1
	v_add_f32_dpp v163, v171, v171 row_ror:8 row_mask:0xf bank_mask:0xc bound_ctrl:1
	v_add_f32_dpp v164, v172, v172 row_ror:8 row_mask:0xf bank_mask:0xc bound_ctrl:1
	v_add_f32_dpp v165, v173, v173 row_ror:8 row_mask:0xf bank_mask:0xc bound_ctrl:1
	v_add_f32_dpp v166, v174, v174 row_ror:8 row_mask:0xf bank_mask:0xc bound_ctrl:1
	v_add_f32_dpp v167, v175, v175 row_ror:8 row_mask:0xf bank_mask:0xc bound_ctrl:1
	v_add_f32_dpp v160, v160, v160 row_half_mirror row_mask:0xf bank_mask:0x5 bound_ctrl:1
	v_add_f32_dpp v161, v161, v161 row_half_mirror row_mask:0xf bank_mask:0x5 bound_ctrl:1
	v_add_f32_dpp v162, v162, v162 row_half_mirror row_mask:0xf bank_mask:0x5 bound_ctrl:1
	v_add_f32_dpp v163, v163, v163 row_half_mirror row_mask:0xf bank_mask:0x5 bound_ctrl:1
	v_add_f32_dpp v160, v164, v164 row_half_mirror row_mask:0xf bank_mask:0xa bound_ctrl:1
	v_add_f32_dpp v161, v165, v165 row_half_mirror row_mask:0xf bank_mask:0xa bound_ctrl:1
	v_add_f32_dpp v162, v166, v166 row_half_mirror row_mask:0xf bank_mask:0xa bound_ctrl:1
	v_add_f32_dpp v163, v167, v167 row_half_mirror row_mask:0xf bank_mask:0xa bound_ctrl:1
	v_and_b32_e32 v188, 2, v44
	v_cmp_ne_u32_e32 vcc, 0, v188
	v_and_b32_e32 v188, 1, v44
	s_nop 0
	v_cndmask_b32_e32 v189, v160, v162, vcc
	v_cndmask_b32_e32 v190, v162, v160, vcc
	v_cndmask_b32_e32 v191, v161, v163, vcc
	v_cndmask_b32_e32 v192, v163, v161, vcc
	v_cmp_ne_u32_e32 vcc, 0, v188
	v_add_f32_dpp v160, v190, v189 quad_perm:[2,3,0,1] row_mask:0xf bank_mask:0xf bound_ctrl:1
	v_add_f32_dpp v161, v192, v191 quad_perm:[2,3,0,1] row_mask:0xf bank_mask:0xf bound_ctrl:1
	v_cndmask_b32_e32 v189, v160, v161, vcc
	v_cndmask_b32_e32 v190, v161, v160, vcc
	s_nop 1
	v_add_f32_dpp v187, v190, v189 quad_perm:[1,0,3,2] row_mask:0xf bank_mask:0xf bound_ctrl:1
	v_fma_f32 v60, v43, v186, v187
	s_lshl_b32 s5, s4, 4
	s_add_i32 s5, s5, s11
	s_cmp_eq_u32 s4, 0
	s_cselect_b32 s5, s10, s5
	v_or_b32_e32 v8, s5, v44
	v_ashrrev_i32_e32 v9, 31, v8
	v_lshlrev_b64 v[8:9], 11, v[8:9]
	v_cvt_pk_bf16_f32 v10, v60, s0
	v_lshl_add_u64 v[8:9], v[28:29], 0, v[8:9]
	global_store_short v[8:9], v10, off
	s_waitcnt lgkmcnt(0)
	s_mov_b64 s[12:13], exec
	s_mov_b64 exec, 1
	ds_add_u32 v193, v195 offset:8
	s_mov_b64 exec, s[12:13]
	v_add_u32_e32 v194, 4, v194
